# v28: GU epilogue blocks 2-7: two column pairs processed together with two temp pairs, +1.0 via v_pk_add_f32 (no s_nop, 52->44 VALU per block)
# speedup vs baseline: 1.0050x; 1.0050x over previous
; #define PG8_LAS __attribute__((address_space(3)))
; __device__ __forceinline__ u32x4 pack8(const f32x4 a, const f32x4 b) { u32x4 w; w.x = cvt_pk_bf16(a[0], a[1]); w.y = cvt_pk_bf16(a[2], a[3]); w.z = cvt_pk_bf16(b[0], b[1]); w.w = cvt_pk_bf16(b[2], b[3]); return w; }
;     __device__ __forceinline__ void operator()(const f32x4 (&acc)[2][2][4][2], const Unit& u, int wr, int wc, int fr, int fq) const {
;         PG8_LAS const float* R = stage_rstd((const float*)(ws + WS_PS), lds, u.pm);
; #pragma unroll
;         for (int ai = 0; ai < 2; ++ai)
; #pragma unroll
;             for (int m = 0; m < 4; ++m) {
;                 const int row = u.pm * BM + ai * HALF + wr * 64 + m * 16 + fr;
;                 const float rs = R[ai * HALF + wr * 64 + m * 16 + fr];
;                 bf16_t* ACT = (bf16_t*)(ws + WS_ACT);
;                 f32x4 a[2];
; #pragma unroll
;                 for (int n = 0; n < 2; ++n) {
;                     const f32x4 g = acc[ai][0][m][n] * rs, uu = acc[ai][1][m][n] * rs;
; #pragma unroll
;                     for (int j = 0; j < 4; ++j) a[n][j] = g[j] * __builtin_amdgcn_rcpf(1.0f + __builtin_amdgcn_exp2f(-1.4426950408889634f * g[j])) * uu[j];
;                 }
;                 *(u32x4*)(ACT + (size_t)row * 2816 + u.pn * 128 + wc * 32 + 8 * fq) = pack8(a[0], a[1]);
;             }
.LBB0_38:
	s_lshl_b32 s3, s48, 8
	ds_read_b32 v146, v142
	v_mov_b32_e32 v145, 0xbfb8aa3b
	s_waitcnt lgkmcnt(0)
	v_pk_mul_f32 v[124:125], v[124:125], v[146:147] op_sel_hi:[1,0]
	v_pk_mul_f32 v[126:127], v[126:127], v[146:147] op_sel_hi:[1,0]
	v_pk_mul_f32 v[116:117], v[116:117], v[146:147] op_sel_hi:[1,0]
	v_pk_mul_f32 v[118:119], v[118:119], v[146:147] op_sel_hi:[1,0]
	v_pk_mul_f32 v[120:121], v[120:121], v[146:147] op_sel_hi:[1,0]
	v_pk_mul_f32 v[122:123], v[122:123], v[146:147] op_sel_hi:[1,0]
	v_pk_mul_f32 v[112:113], v[112:113], v[146:147] op_sel_hi:[1,0]
	v_pk_mul_f32 v[114:115], v[114:115], v[146:147] op_sel_hi:[1,0]
	v_pk_mul_f32 v[148:149], v[124:125], v[144:145] op_sel:[0,1] op_sel_hi:[1,1]
	v_exp_f32_e32 v148, v148
	v_exp_f32_e32 v149, v149
	v_add_f32_e32 v148, 1.0, v148
	v_add_f32_e32 v149, 1.0, v149
	v_rcp_f32_e32 v148, v148
	v_rcp_f32_e32 v149, v149
	s_nop 0
	v_pk_mul_f32 v[124:125], v[124:125], v[148:149]
	v_pk_mul_f32 v[120:121], v[120:121], v[124:125]
	v_pk_mul_f32 v[148:149], v[126:127], v[144:145] op_sel:[0,1] op_sel_hi:[1,1]
	v_exp_f32_e32 v148, v148
	v_exp_f32_e32 v149, v149
	v_add_f32_e32 v148, 1.0, v148
	v_add_f32_e32 v149, 1.0, v149
	v_rcp_f32_e32 v148, v148
	v_rcp_f32_e32 v149, v149
	s_nop 0
	v_pk_mul_f32 v[126:127], v[126:127], v[148:149]
	v_pk_mul_f32 v[122:123], v[122:123], v[126:127]
	v_pk_mul_f32 v[148:149], v[116:117], v[144:145] op_sel:[0,1] op_sel_hi:[1,1]
	v_exp_f32_e32 v148, v148
	v_exp_f32_e32 v149, v149
	v_add_f32_e32 v148, 1.0, v148
	v_add_f32_e32 v149, 1.0, v149
	v_rcp_f32_e32 v148, v148
	v_rcp_f32_e32 v149, v149
	s_nop 0
	v_pk_mul_f32 v[116:117], v[116:117], v[148:149]
	v_pk_mul_f32 v[112:113], v[112:113], v[116:117]
	v_pk_mul_f32 v[148:149], v[118:119], v[144:145] op_sel:[0,1] op_sel_hi:[1,1]
	v_exp_f32_e32 v148, v148
	v_exp_f32_e32 v149, v149
	v_add_f32_e32 v148, 1.0, v148
	v_add_f32_e32 v149, 1.0, v149
	v_rcp_f32_e32 v148, v148
	v_rcp_f32_e32 v149, v149
	s_nop 0
	v_pk_mul_f32 v[118:119], v[118:119], v[148:149]
	v_pk_mul_f32 v[114:115], v[114:115], v[118:119]
	v_cvt_pk_bf16_f32 v116, v112, v113
	v_cvt_pk_bf16_f32 v117, v114, v115
	v_cvt_pk_bf16_f32 v114, v120, v121
	v_cvt_pk_bf16_f32 v115, v122, v123
	s_lshl_b32 s0, s47, 7
	v_add_u32_e32 v144, s3, v140
	s_ashr_i32 s1, s0, 31
	s_movk_i32 s3, 0x1600
	s_lshl_b64 s[0:1], s[0:1], 1
	s_andn2_b64 vcc, exec, s[36:37]
	v_mov_b64_e32 v[112:113], s[16:17]
	s_mov_b32 s101, 0
	v_mad_i64_i32 v[118:119], s[4:5], v144, s3, v[112:113]
	v_lshl_add_u64 v[118:119], v[118:119], 0, s[0:1]
	v_lshl_add_u64 v[118:119], v[118:119], 0, s[34:35]
	v_lshl_add_u64 v[118:119], v[118:119], 0, v[184:185]
	global_store_dwordx4 v[118:119], v[114:117], off
	ds_read_b32 v114, v142 offset:64
	ds_read_b32 v120, v142 offset:128
	ds_read_b32 v122, v142 offset:192
	ds_read_b32 v124, v142 offset:512
	ds_read_b32 v126, v142 offset:576
	ds_read_b32 v112, v142 offset:640
	ds_read_b32 v116, v142 offset:704
	v_mov_b32_e32 v146, 1.0
	s_waitcnt lgkmcnt(6)
	v_pk_mul_f32 v[108:109], v[108:109], v[114:115] op_sel_hi:[1,0]
	v_pk_mul_f32 v[110:111], v[110:111], v[114:115] op_sel_hi:[1,0]
	v_pk_mul_f32 v[100:101], v[100:101], v[114:115] op_sel_hi:[1,0]
	v_pk_mul_f32 v[102:103], v[102:103], v[114:115] op_sel_hi:[1,0]
	v_pk_mul_f32 v[104:105], v[104:105], v[114:115] op_sel_hi:[1,0]
	v_pk_mul_f32 v[106:107], v[106:107], v[114:115] op_sel_hi:[1,0]
	v_pk_mul_f32 v[96:97], v[96:97], v[114:115] op_sel_hi:[1,0]
	v_pk_mul_f32 v[98:99], v[98:99], v[114:115] op_sel_hi:[1,0]
	v_pk_mul_f32 v[148:149], v[108:109], v[144:145] op_sel:[0,1] op_sel_hi:[1,1]
	v_exp_f32_e32 v148, v148
	v_exp_f32_e32 v149, v149
	v_add_f32_e32 v148, 1.0, v148
	v_add_f32_e32 v149, 1.0, v149
	v_rcp_f32_e32 v148, v148
	v_rcp_f32_e32 v149, v149
	s_nop 0
	v_pk_mul_f32 v[108:109], v[108:109], v[148:149]
	v_pk_mul_f32 v[104:105], v[104:105], v[108:109]
	v_pk_mul_f32 v[148:149], v[110:111], v[144:145] op_sel:[0,1] op_sel_hi:[1,1]
	v_exp_f32_e32 v148, v148
	v_exp_f32_e32 v149, v149
	v_add_f32_e32 v148, 1.0, v148
	v_add_f32_e32 v149, 1.0, v149
	v_rcp_f32_e32 v148, v148
	v_rcp_f32_e32 v149, v149
	s_nop 0
	v_pk_mul_f32 v[110:111], v[110:111], v[148:149]
	v_pk_mul_f32 v[106:107], v[106:107], v[110:111]
	v_pk_mul_f32 v[148:149], v[100:101], v[144:145] op_sel:[0,1] op_sel_hi:[1,1]
	v_exp_f32_e32 v148, v148
	v_exp_f32_e32 v149, v149
	v_add_f32_e32 v148, 1.0, v148
	v_add_f32_e32 v149, 1.0, v149
	v_rcp_f32_e32 v148, v148
	v_rcp_f32_e32 v149, v149
	s_nop 0
	v_pk_mul_f32 v[100:101], v[100:101], v[148:149]
	v_pk_mul_f32 v[96:97], v[96:97], v[100:101]
	v_pk_mul_f32 v[148:149], v[102:103], v[144:145] op_sel:[0,1] op_sel_hi:[1,1]
	v_exp_f32_e32 v148, v148
	v_exp_f32_e32 v149, v149
	v_add_f32_e32 v148, 1.0, v148
	v_add_f32_e32 v149, 1.0, v149
	v_rcp_f32_e32 v148, v148
	v_rcp_f32_e32 v149, v149
	s_nop 0
	v_pk_mul_f32 v[102:103], v[102:103], v[148:149]
	v_pk_mul_f32 v[98:99], v[98:99], v[102:103]
	v_cvt_pk_bf16_f32 v99, v98, v99
	v_cvt_pk_bf16_f32 v98, v96, v97
	v_cvt_pk_bf16_f32 v96, v104, v105
	v_cvt_pk_bf16_f32 v97, v106, v107
	s_mov_b32 s100, 0x16000
	v_lshl_add_u64 v[100:101], v[118:119], 0, s[100:101]
	global_store_dwordx4 v[100:101], v[96:99], off
	s_waitcnt lgkmcnt(0)
; __device__ __forceinline__ u32x4 pack8(const f32x4 a, const f32x4 b) { u32x4 w; w.x = cvt_pk_bf16(a[0], a[1]); w.y = cvt_pk_bf16(a[2], a[3]); w.z = cvt_pk_bf16(b[0], b[1]); w.w = cvt_pk_bf16(b[2], b[3]); return w; }
;     __device__ __forceinline__ void operator()(const f32x4 (&acc)[2][2][4][2], const Unit& u, int wr, int wc, int fr, int fq) const {
;     ...
;         for (int ai = 0; ai < 2; ++ai)
; #pragma unroll
;             for (int m = 0; m < 4; ++m) {
;                 const int row = u.pm * BM + ai * HALF + wr * 64 + m * 16 + fr;
;                 const float rs = R[ai * HALF + wr * 64 + m * 16 + fr];
;                 bf16_t* ACT = (bf16_t*)(ws + WS_ACT);
;                 f32x4 a[2];
; #pragma unroll
;                 for (int n = 0; n < 2; ++n) {
;                     const f32x4 g = acc[ai][0][m][n] * rs, uu = acc[ai][1][m][n] * rs;
; #pragma unroll
;                     for (int j = 0; j < 4; ++j) a[n][j] = g[j] * __builtin_amdgcn_rcpf(1.0f + __builtin_amdgcn_exp2f(-1.4426950408889634f * g[j])) * uu[j];
;                 }
;                 *(u32x4*)(ACT + (size_t)row * 2816 + u.pn * 128 + wc * 32 + 8 * fq) = pack8(a[0], a[1]);
;             }
	v_pk_mul_f32 v[92:93], v[92:93], v[120:121] op_sel_hi:[1,0]
	v_pk_mul_f32 v[94:95], v[94:95], v[120:121] op_sel_hi:[1,0]
	v_pk_mul_f32 v[84:85], v[84:85], v[120:121] op_sel_hi:[1,0]
	v_pk_mul_f32 v[86:87], v[86:87], v[120:121] op_sel_hi:[1,0]
	v_pk_mul_f32 v[88:89], v[88:89], v[120:121] op_sel_hi:[1,0]
	v_pk_mul_f32 v[90:91], v[90:91], v[120:121] op_sel_hi:[1,0]
	v_pk_mul_f32 v[80:81], v[80:81], v[120:121] op_sel_hi:[1,0]
	v_pk_mul_f32 v[82:83], v[82:83], v[120:121] op_sel_hi:[1,0]
	v_pk_mul_f32 v[148:149], v[92:93], v[144:145] op_sel:[0,1] op_sel_hi:[1,1]
	v_pk_mul_f32 v[114:115], v[94:95], v[144:145] op_sel:[0,1] op_sel_hi:[1,1]
	v_exp_f32_e32 v148, v148
	v_exp_f32_e32 v149, v149
	v_exp_f32_e32 v114, v114
	v_exp_f32_e32 v115, v115
	v_pk_add_f32 v[148:149], v[148:149], v[146:147] op_sel_hi:[1,0]
	v_pk_add_f32 v[114:115], v[114:115], v[146:147] op_sel_hi:[1,0]
	v_rcp_f32_e32 v148, v148
	v_rcp_f32_e32 v149, v149
	v_rcp_f32_e32 v114, v114
	v_rcp_f32_e32 v115, v115
	v_pk_mul_f32 v[92:93], v[92:93], v[148:149]
	v_pk_mul_f32 v[94:95], v[94:95], v[114:115]
	v_pk_mul_f32 v[88:89], v[88:89], v[92:93]
	v_pk_mul_f32 v[90:91], v[90:91], v[94:95]
	v_pk_mul_f32 v[148:149], v[84:85], v[144:145] op_sel:[0,1] op_sel_hi:[1,1]
	v_pk_mul_f32 v[114:115], v[86:87], v[144:145] op_sel:[0,1] op_sel_hi:[1,1]
	v_exp_f32_e32 v148, v148
	v_exp_f32_e32 v149, v149
	v_exp_f32_e32 v114, v114
	v_exp_f32_e32 v115, v115
	v_pk_add_f32 v[148:149], v[148:149], v[146:147] op_sel_hi:[1,0]
	v_pk_add_f32 v[114:115], v[114:115], v[146:147] op_sel_hi:[1,0]
	v_rcp_f32_e32 v148, v148
	v_rcp_f32_e32 v149, v149
	v_rcp_f32_e32 v114, v114
	v_rcp_f32_e32 v115, v115
	v_pk_mul_f32 v[84:85], v[84:85], v[148:149]
	v_pk_mul_f32 v[86:87], v[86:87], v[114:115]
	v_pk_mul_f32 v[80:81], v[80:81], v[84:85]
	v_pk_mul_f32 v[82:83], v[82:83], v[86:87]
	v_cvt_pk_bf16_f32 v83, v82, v83
	v_cvt_pk_bf16_f32 v82, v80, v81
	v_cvt_pk_bf16_f32 v80, v88, v89
	v_cvt_pk_bf16_f32 v81, v90, v91
	s_mov_b32 s100, 0x2c000
	v_lshl_add_u64 v[84:85], v[118:119], 0, s[100:101]
	global_store_dwordx4 v[84:85], v[80:83], off
	s_waitcnt lgkmcnt(0)
	v_pk_mul_f32 v[76:77], v[76:77], v[122:123] op_sel_hi:[1,0]
	v_pk_mul_f32 v[78:79], v[78:79], v[122:123] op_sel_hi:[1,0]
	v_pk_mul_f32 v[68:69], v[68:69], v[122:123] op_sel_hi:[1,0]
	v_pk_mul_f32 v[70:71], v[70:71], v[122:123] op_sel_hi:[1,0]
	v_pk_mul_f32 v[72:73], v[72:73], v[122:123] op_sel_hi:[1,0]
	v_pk_mul_f32 v[74:75], v[74:75], v[122:123] op_sel_hi:[1,0]
	v_pk_mul_f32 v[64:65], v[64:65], v[122:123] op_sel_hi:[1,0]
	v_pk_mul_f32 v[66:67], v[66:67], v[122:123] op_sel_hi:[1,0]
	v_pk_mul_f32 v[148:149], v[76:77], v[144:145] op_sel:[0,1] op_sel_hi:[1,1]
	v_pk_mul_f32 v[114:115], v[78:79], v[144:145] op_sel:[0,1] op_sel_hi:[1,1]
	v_exp_f32_e32 v148, v148
	v_exp_f32_e32 v149, v149
	v_exp_f32_e32 v114, v114
	v_exp_f32_e32 v115, v115
	v_pk_add_f32 v[148:149], v[148:149], v[146:147] op_sel_hi:[1,0]
	v_pk_add_f32 v[114:115], v[114:115], v[146:147] op_sel_hi:[1,0]
	v_rcp_f32_e32 v148, v148
	v_rcp_f32_e32 v149, v149
	v_rcp_f32_e32 v114, v114
	v_rcp_f32_e32 v115, v115
	v_pk_mul_f32 v[76:77], v[76:77], v[148:149]
	v_pk_mul_f32 v[78:79], v[78:79], v[114:115]
	v_pk_mul_f32 v[72:73], v[72:73], v[76:77]
	v_pk_mul_f32 v[74:75], v[74:75], v[78:79]
	v_pk_mul_f32 v[148:149], v[68:69], v[144:145] op_sel:[0,1] op_sel_hi:[1,1]
	v_pk_mul_f32 v[114:115], v[70:71], v[144:145] op_sel:[0,1] op_sel_hi:[1,1]
	v_exp_f32_e32 v148, v148
	v_exp_f32_e32 v149, v149
	v_exp_f32_e32 v114, v114
	v_exp_f32_e32 v115, v115
	v_pk_add_f32 v[148:149], v[148:149], v[146:147] op_sel_hi:[1,0]
	v_pk_add_f32 v[114:115], v[114:115], v[146:147] op_sel_hi:[1,0]
	v_rcp_f32_e32 v148, v148
	v_rcp_f32_e32 v149, v149
	v_rcp_f32_e32 v114, v114
	v_rcp_f32_e32 v115, v115
	v_pk_mul_f32 v[68:69], v[68:69], v[148:149]
	v_pk_mul_f32 v[70:71], v[70:71], v[114:115]
	v_pk_mul_f32 v[64:65], v[64:65], v[68:69]
	v_pk_mul_f32 v[66:67], v[66:67], v[70:71]
	v_cvt_pk_bf16_f32 v67, v66, v67
	v_cvt_pk_bf16_f32 v66, v64, v65
	v_cvt_pk_bf16_f32 v64, v72, v73
	v_cvt_pk_bf16_f32 v65, v74, v75
	s_mov_b32 s100, 0x42000
	v_lshl_add_u64 v[68:69], v[118:119], 0, s[100:101]
	global_store_dwordx4 v[68:69], v[64:67], off
	s_waitcnt lgkmcnt(0)
	v_pk_mul_f32 v[60:61], v[60:61], v[124:125] op_sel_hi:[1,0]
	v_pk_mul_f32 v[62:63], v[62:63], v[124:125] op_sel_hi:[1,0]
	v_pk_mul_f32 v[52:53], v[52:53], v[124:125] op_sel_hi:[1,0]
	v_pk_mul_f32 v[54:55], v[54:55], v[124:125] op_sel_hi:[1,0]
	v_pk_mul_f32 v[56:57], v[56:57], v[124:125] op_sel_hi:[1,0]
	v_pk_mul_f32 v[58:59], v[58:59], v[124:125] op_sel_hi:[1,0]
	v_pk_mul_f32 v[48:49], v[48:49], v[124:125] op_sel_hi:[1,0]
	v_pk_mul_f32 v[50:51], v[50:51], v[124:125] op_sel_hi:[1,0]
	v_pk_mul_f32 v[148:149], v[60:61], v[144:145] op_sel:[0,1] op_sel_hi:[1,1]
	v_pk_mul_f32 v[114:115], v[62:63], v[144:145] op_sel:[0,1] op_sel_hi:[1,1]
	v_exp_f32_e32 v148, v148
	v_exp_f32_e32 v149, v149
	v_exp_f32_e32 v114, v114
	v_exp_f32_e32 v115, v115
	v_pk_add_f32 v[148:149], v[148:149], v[146:147] op_sel_hi:[1,0]
	v_pk_add_f32 v[114:115], v[114:115], v[146:147] op_sel_hi:[1,0]
	v_rcp_f32_e32 v148, v148
	v_rcp_f32_e32 v149, v149
	v_rcp_f32_e32 v114, v114
	v_rcp_f32_e32 v115, v115
	v_pk_mul_f32 v[60:61], v[60:61], v[148:149]
	v_pk_mul_f32 v[62:63], v[62:63], v[114:115]
	v_pk_mul_f32 v[56:57], v[56:57], v[60:61]
	v_pk_mul_f32 v[58:59], v[58:59], v[62:63]
	v_pk_mul_f32 v[148:149], v[52:53], v[144:145] op_sel:[0,1] op_sel_hi:[1,1]
	v_pk_mul_f32 v[114:115], v[54:55], v[144:145] op_sel:[0,1] op_sel_hi:[1,1]
	v_exp_f32_e32 v148, v148
	v_exp_f32_e32 v149, v149
	v_exp_f32_e32 v114, v114
	v_exp_f32_e32 v115, v115
	v_pk_add_f32 v[148:149], v[148:149], v[146:147] op_sel_hi:[1,0]
	v_pk_add_f32 v[114:115], v[114:115], v[146:147] op_sel_hi:[1,0]
	v_rcp_f32_e32 v148, v148
	v_rcp_f32_e32 v149, v149
	v_rcp_f32_e32 v114, v114
	v_rcp_f32_e32 v115, v115
	v_pk_mul_f32 v[52:53], v[52:53], v[148:149]
	v_pk_mul_f32 v[54:55], v[54:55], v[114:115]
	v_pk_mul_f32 v[48:49], v[48:49], v[52:53]
	v_pk_mul_f32 v[50:51], v[50:51], v[54:55]
	v_cvt_pk_bf16_f32 v51, v50, v51
	v_cvt_pk_bf16_f32 v50, v48, v49
	v_cvt_pk_bf16_f32 v48, v56, v57
	v_cvt_pk_bf16_f32 v49, v58, v59
	s_mov_b32 s100, 0xb0000
	v_lshl_add_u64 v[52:53], v[118:119], 0, s[100:101]
	global_store_dwordx4 v[52:53], v[48:51], off
	s_waitcnt lgkmcnt(0)
; __device__ __forceinline__ u32x4 pack8(const f32x4 a, const f32x4 b) { u32x4 w; w.x = cvt_pk_bf16(a[0], a[1]); w.y = cvt_pk_bf16(a[2], a[3]); w.z = cvt_pk_bf16(b[0], b[1]); w.w = cvt_pk_bf16(b[2], b[3]); return w; }
;     __device__ __forceinline__ void operator()(const f32x4 (&acc)[2][2][4][2], const Unit& u, int wr, int wc, int fr, int fq) const {
;     ...
;         for (int ai = 0; ai < 2; ++ai)
; #pragma unroll
;             for (int m = 0; m < 4; ++m) {
;                 const int row = u.pm * BM + ai * HALF + wr * 64 + m * 16 + fr;
;                 const float rs = R[ai * HALF + wr * 64 + m * 16 + fr];
;                 bf16_t* ACT = (bf16_t*)(ws + WS_ACT);
;                 f32x4 a[2];
; #pragma unroll
;                 for (int n = 0; n < 2; ++n) {
;                     const f32x4 g = acc[ai][0][m][n] * rs, uu = acc[ai][1][m][n] * rs;
; #pragma unroll
;                     for (int j = 0; j < 4; ++j) a[n][j] = g[j] * __builtin_amdgcn_rcpf(1.0f + __builtin_amdgcn_exp2f(-1.4426950408889634f * g[j])) * uu[j];
;                 }
;                 *(u32x4*)(ACT + (size_t)row * 2816 + u.pn * 128 + wc * 32 + 8 * fq) = pack8(a[0], a[1]);
;             }
	v_pk_mul_f32 v[44:45], v[44:45], v[126:127] op_sel_hi:[1,0]
	v_pk_mul_f32 v[46:47], v[46:47], v[126:127] op_sel_hi:[1,0]
	v_pk_mul_f32 v[36:37], v[36:37], v[126:127] op_sel_hi:[1,0]
	v_pk_mul_f32 v[38:39], v[38:39], v[126:127] op_sel_hi:[1,0]
	v_pk_mul_f32 v[40:41], v[40:41], v[126:127] op_sel_hi:[1,0]
	v_pk_mul_f32 v[42:43], v[42:43], v[126:127] op_sel_hi:[1,0]
	v_pk_mul_f32 v[32:33], v[32:33], v[126:127] op_sel_hi:[1,0]
	v_pk_mul_f32 v[34:35], v[34:35], v[126:127] op_sel_hi:[1,0]
	v_pk_mul_f32 v[148:149], v[44:45], v[144:145] op_sel:[0,1] op_sel_hi:[1,1]
	v_pk_mul_f32 v[114:115], v[46:47], v[144:145] op_sel:[0,1] op_sel_hi:[1,1]
	v_exp_f32_e32 v148, v148
	v_exp_f32_e32 v149, v149
	v_exp_f32_e32 v114, v114
	v_exp_f32_e32 v115, v115
	v_pk_add_f32 v[148:149], v[148:149], v[146:147] op_sel_hi:[1,0]
	v_pk_add_f32 v[114:115], v[114:115], v[146:147] op_sel_hi:[1,0]
	v_rcp_f32_e32 v148, v148
	v_rcp_f32_e32 v149, v149
	v_rcp_f32_e32 v114, v114
	v_rcp_f32_e32 v115, v115
	v_pk_mul_f32 v[44:45], v[44:45], v[148:149]
	v_pk_mul_f32 v[46:47], v[46:47], v[114:115]
	v_pk_mul_f32 v[40:41], v[40:41], v[44:45]
	v_pk_mul_f32 v[42:43], v[42:43], v[46:47]
	v_pk_mul_f32 v[148:149], v[36:37], v[144:145] op_sel:[0,1] op_sel_hi:[1,1]
	v_pk_mul_f32 v[114:115], v[38:39], v[144:145] op_sel:[0,1] op_sel_hi:[1,1]
	v_exp_f32_e32 v148, v148
	v_exp_f32_e32 v149, v149
	v_exp_f32_e32 v114, v114
	v_exp_f32_e32 v115, v115
	v_pk_add_f32 v[148:149], v[148:149], v[146:147] op_sel_hi:[1,0]
	v_pk_add_f32 v[114:115], v[114:115], v[146:147] op_sel_hi:[1,0]
	v_rcp_f32_e32 v148, v148
	v_rcp_f32_e32 v149, v149
	v_rcp_f32_e32 v114, v114
	v_rcp_f32_e32 v115, v115
	v_pk_mul_f32 v[36:37], v[36:37], v[148:149]
	v_pk_mul_f32 v[38:39], v[38:39], v[114:115]
	v_pk_mul_f32 v[32:33], v[32:33], v[36:37]
	v_pk_mul_f32 v[34:35], v[34:35], v[38:39]
	v_cvt_pk_bf16_f32 v35, v34, v35
	v_cvt_pk_bf16_f32 v34, v32, v33
	v_cvt_pk_bf16_f32 v32, v40, v41
	v_cvt_pk_bf16_f32 v33, v42, v43
	s_mov_b32 s100, 0xc6000
	v_lshl_add_u64 v[36:37], v[118:119], 0, s[100:101]
	global_store_dwordx4 v[36:37], v[32:35], off
	s_waitcnt lgkmcnt(0)
	v_pk_mul_f32 v[28:29], v[28:29], v[112:113] op_sel_hi:[1,0]
	v_pk_mul_f32 v[30:31], v[30:31], v[112:113] op_sel_hi:[1,0]
	v_pk_mul_f32 v[20:21], v[20:21], v[112:113] op_sel_hi:[1,0]
	v_pk_mul_f32 v[22:23], v[22:23], v[112:113] op_sel_hi:[1,0]
	v_pk_mul_f32 v[24:25], v[24:25], v[112:113] op_sel_hi:[1,0]
	v_pk_mul_f32 v[26:27], v[26:27], v[112:113] op_sel_hi:[1,0]
	v_pk_mul_f32 v[16:17], v[16:17], v[112:113] op_sel_hi:[1,0]
	v_pk_mul_f32 v[18:19], v[18:19], v[112:113] op_sel_hi:[1,0]
	v_pk_mul_f32 v[148:149], v[28:29], v[144:145] op_sel:[0,1] op_sel_hi:[1,1]
	v_pk_mul_f32 v[114:115], v[30:31], v[144:145] op_sel:[0,1] op_sel_hi:[1,1]
	v_exp_f32_e32 v148, v148
	v_exp_f32_e32 v149, v149
	v_exp_f32_e32 v114, v114
	v_exp_f32_e32 v115, v115
	v_pk_add_f32 v[148:149], v[148:149], v[146:147] op_sel_hi:[1,0]
	v_pk_add_f32 v[114:115], v[114:115], v[146:147] op_sel_hi:[1,0]
	v_rcp_f32_e32 v148, v148
	v_rcp_f32_e32 v149, v149
	v_rcp_f32_e32 v114, v114
	v_rcp_f32_e32 v115, v115
	v_pk_mul_f32 v[28:29], v[28:29], v[148:149]
	v_pk_mul_f32 v[30:31], v[30:31], v[114:115]
	v_pk_mul_f32 v[24:25], v[24:25], v[28:29]
	v_pk_mul_f32 v[26:27], v[26:27], v[30:31]
	v_pk_mul_f32 v[148:149], v[20:21], v[144:145] op_sel:[0,1] op_sel_hi:[1,1]
	v_pk_mul_f32 v[114:115], v[22:23], v[144:145] op_sel:[0,1] op_sel_hi:[1,1]
	v_exp_f32_e32 v148, v148
	v_exp_f32_e32 v149, v149
	v_exp_f32_e32 v114, v114
	v_exp_f32_e32 v115, v115
	v_pk_add_f32 v[148:149], v[148:149], v[146:147] op_sel_hi:[1,0]
	v_pk_add_f32 v[114:115], v[114:115], v[146:147] op_sel_hi:[1,0]
	v_rcp_f32_e32 v148, v148
	v_rcp_f32_e32 v149, v149
	v_rcp_f32_e32 v114, v114
	v_rcp_f32_e32 v115, v115
	v_pk_mul_f32 v[20:21], v[20:21], v[148:149]
	v_pk_mul_f32 v[22:23], v[22:23], v[114:115]
	v_pk_mul_f32 v[16:17], v[16:17], v[20:21]
	v_pk_mul_f32 v[18:19], v[18:19], v[22:23]
	v_cvt_pk_bf16_f32 v19, v18, v19
	v_cvt_pk_bf16_f32 v18, v16, v17
	v_cvt_pk_bf16_f32 v16, v24, v25
	v_cvt_pk_bf16_f32 v17, v26, v27
	s_mov_b32 s100, 0xdc000
	v_lshl_add_u64 v[20:21], v[118:119], 0, s[100:101]
	global_store_dwordx4 v[20:21], v[16:19], off
	s_waitcnt lgkmcnt(0)
	v_pk_mul_f32 v[12:13], v[12:13], v[116:117] op_sel_hi:[1,0]
	v_pk_mul_f32 v[14:15], v[14:15], v[116:117] op_sel_hi:[1,0]
	v_pk_mul_f32 v[4:5], v[4:5], v[116:117] op_sel_hi:[1,0]
	v_pk_mul_f32 v[6:7], v[6:7], v[116:117] op_sel_hi:[1,0]
	v_pk_mul_f32 v[8:9], v[8:9], v[116:117] op_sel_hi:[1,0]
	v_pk_mul_f32 v[10:11], v[10:11], v[116:117] op_sel_hi:[1,0]
	v_pk_mul_f32 v[0:1], v[0:1], v[116:117] op_sel_hi:[1,0]
	v_pk_mul_f32 v[2:3], v[2:3], v[116:117] op_sel_hi:[1,0]
	v_pk_mul_f32 v[148:149], v[12:13], v[144:145] op_sel:[0,1] op_sel_hi:[1,1]
	v_pk_mul_f32 v[114:115], v[14:15], v[144:145] op_sel:[0,1] op_sel_hi:[1,1]
	v_exp_f32_e32 v148, v148
	v_exp_f32_e32 v149, v149
	v_exp_f32_e32 v114, v114
	v_exp_f32_e32 v115, v115
	v_pk_add_f32 v[148:149], v[148:149], v[146:147] op_sel_hi:[1,0]
	v_pk_add_f32 v[114:115], v[114:115], v[146:147] op_sel_hi:[1,0]
	v_rcp_f32_e32 v148, v148
	v_rcp_f32_e32 v149, v149
	v_rcp_f32_e32 v114, v114
	v_rcp_f32_e32 v115, v115
	v_pk_mul_f32 v[12:13], v[12:13], v[148:149]
	v_pk_mul_f32 v[14:15], v[14:15], v[114:115]
	v_pk_mul_f32 v[8:9], v[8:9], v[12:13]
	v_pk_mul_f32 v[10:11], v[10:11], v[14:15]
	v_pk_mul_f32 v[148:149], v[4:5], v[144:145] op_sel:[0,1] op_sel_hi:[1,1]
	v_pk_mul_f32 v[114:115], v[6:7], v[144:145] op_sel:[0,1] op_sel_hi:[1,1]
	v_exp_f32_e32 v148, v148
	v_exp_f32_e32 v149, v149
	v_exp_f32_e32 v114, v114
	v_exp_f32_e32 v115, v115
	v_pk_add_f32 v[148:149], v[148:149], v[146:147] op_sel_hi:[1,0]
	v_pk_add_f32 v[114:115], v[114:115], v[146:147] op_sel_hi:[1,0]
	v_rcp_f32_e32 v148, v148
	v_rcp_f32_e32 v149, v149
	v_rcp_f32_e32 v114, v114
	v_rcp_f32_e32 v115, v115
	v_pk_mul_f32 v[4:5], v[4:5], v[148:149]
	v_pk_mul_f32 v[6:7], v[6:7], v[114:115]
	v_pk_mul_f32 v[0:1], v[0:1], v[4:5]
	v_pk_mul_f32 v[2:3], v[2:3], v[6:7]
	v_cvt_pk_bf16_f32 v3, v2, v3
	v_cvt_pk_bf16_f32 v2, v0, v1
	v_cvt_pk_bf16_f32 v0, v8, v9
	v_cvt_pk_bf16_f32 v1, v10, v11
	s_mov_b32 s100, 0xf2000
	v_lshl_add_u64 v[4:5], v[118:119], 0, s[100:101]
	s_mov_b64 s[0:1], -1
	global_store_dwordx4 v[4:5], v[0:3], off
	s_cbranch_vccnz .LBB0_31
	s_andn2_b64 vcc, exec, s[8:9]
	s_cbranch_vccnz .LBB0_30
	s_barrier
	s_branch .LBB0_30
